# speedup vs baseline: 1.0172x; 1.0005x over previous
; __device__ __forceinline__ float bflo(unsigned w) { return __uint_as_float(w << 16); }
; __device__ __forceinline__ float bfhi(unsigned w) { return __uint_as_float(w & 0xffff0000u); }
; template <int MODE, bool PRE = false, bool NEXT = false> ...
;     ...
;       } else if constexpr (MODE == EP_RES) {
;         float* orow = (float*)e.out + (long)row * e.ldo + cbase;
;         const float* arow = (const float*)e.aux + (long)row * e.ldaux + cbase;
;         const u16* brow = (const u16*)e.aux + (long)row * e.ldaux + cbase;
;         u16* xrow = e.xb + (long)row * 1024 + cbase;
;         float part = 0.f;
; #pragma unroll
;         for (int bj = 0; bj < 2; ++bj)
; #pragma unroll
;           for (int n = 0; n < 2; ++n) {
;             f32x4 a;
;             if (e.auxbf) { const u32x2 w = *reinterpret_cast<const u32x2*>(brow + bj * 128 + n * 16); a = f32x4{bflo(w[0]), bfhi(w[0]), bflo(w[1]), bfhi(w[1])}; }
;             else a = *reinterpret_cast<const f32x4*>(arow + bj * 128 + n * 16);
;             a += acc[ai][bj][m][n];
;             if (e.out) *reinterpret_cast<f32x4*>(orow + bj * 128 + n * 16) = a;
;             if (e.xb) {
;               u32x2 w = {cvtpk(a[0], a[1]), cvtpk(a[2], a[3])};
;               *reinterpret_cast<u32x2*>(xrow + bj * 128 + n * 16) = w;
;               part += a[0] * a[0] + a[1] * a[1] + a[2] * a[2] + a[3] * a[3];
;             }
;           }
;         if (e.xb) {
;           part += __int_as_float(__builtin_amdgcn_ds_bpermute((lane ^ 16) << 2, __float_as_int(part)));
;           part += __int_as_float(__builtin_amdgcn_ds_bpermute((lane ^ 32) << 2, __float_as_int(part)));
;           if (fq == 0) reinterpret_cast<float*>(g_lds)[row * 4 + wc] = part;
;         }
.LBB0_969:
	v_readlane_b32 s10, v254, 57
	v_readlane_b32 s11, v254, 58
	v_readfirstlane_b32 s8, v130
	v_mov_b32_e32 v0, 1.0
	s_andn2_b64 vcc, exec, s[10:11]
	s_mov_b32 s59, 0x42b504f3
	s_cbranch_vccnz .LBB0_958
	s_lshl_b64 s[10:11], s[6:7], 19
	v_readlane_b32 s9, v253, 58
	s_add_u32 s9, s9, s10
	v_readlane_b32 s10, v253, 59
	s_addc_u32 s12, s10, s11
	s_lshl_b32 s10, s0, 8
	s_ashr_i32 s11, s10, 31
	s_lshl_b64 s[10:11], s[10:11], 1
	s_add_u32 s10, s9, s10
	s_addc_u32 s11, s12, s11
	s_bfe_u32 s9, s8, 0x20006
	s_ashr_i32 s8, s8, 2
	s_andn2_b32 s8, s8, 63
	v_lshrrev_b32_e32 v0, 1, v130
	v_or_b32_e32 v132, s8, v143
	v_and_b32_e32 v0, 24, v0
	v_lshl_or_b32 v0, s9, 6, v0
	v_ashrrev_i32_e32 v133, 31, v132
	v_lshl_add_u64 v[134:135], s[10:11], 0, v[0:1]
	v_lshlrev_b64 v[136:137], 11, v[132:133]
	v_lshl_add_u64 v[136:137], v[134:135], 0, v[136:137]
	v_mov_b32_e32 v161, 0
	v_mov_b32_e32 v160, v132
	v_lshlrev_b32_e32 v160, 11, v160
	v_lshl_add_u64 v[162:163], v[134:135], 0, v[160:161]
	global_load_dwordx2 v[192:193], v[162:163], off
	global_load_dwordx2 v[194:195], v[162:163], off offset:32
	global_load_dwordx2 v[196:197], v[162:163], off offset:256
	global_load_dwordx2 v[198:199], v[162:163], off offset:288
	v_add_u32_e32 v160, 0x10, v132
	v_lshlrev_b32_e32 v160, 11, v160
	v_lshl_add_u64 v[162:163], v[134:135], 0, v[160:161]
	global_load_dwordx2 v[200:201], v[162:163], off
	global_load_dwordx2 v[202:203], v[162:163], off offset:32
	global_load_dwordx2 v[204:205], v[162:163], off offset:256
	global_load_dwordx2 v[206:207], v[162:163], off offset:288
	v_add_u32_e32 v160, 0x20, v132
	v_lshlrev_b32_e32 v160, 11, v160
	v_lshl_add_u64 v[162:163], v[134:135], 0, v[160:161]
	global_load_dwordx2 v[208:209], v[162:163], off
	global_load_dwordx2 v[210:211], v[162:163], off offset:32
	global_load_dwordx2 v[212:213], v[162:163], off offset:256
	global_load_dwordx2 v[214:215], v[162:163], off offset:288
	v_add_u32_e32 v160, 0x30, v132
	v_lshlrev_b32_e32 v160, 11, v160
	v_lshl_add_u64 v[162:163], v[134:135], 0, v[160:161]
	global_load_dwordx2 v[216:217], v[162:163], off
	global_load_dwordx2 v[218:219], v[162:163], off offset:32
	global_load_dwordx2 v[220:221], v[162:163], off offset:256
	global_load_dwordx2 v[222:223], v[162:163], off offset:288
	v_add_u32_e32 v160, 0x80, v132
	v_lshlrev_b32_e32 v160, 11, v160
	v_lshl_add_u64 v[162:163], v[134:135], 0, v[160:161]
	global_load_dwordx2 v[224:225], v[162:163], off
	global_load_dwordx2 v[226:227], v[162:163], off offset:32
	global_load_dwordx2 v[228:229], v[162:163], off offset:256
	global_load_dwordx2 v[230:231], v[162:163], off offset:288
	v_add_u32_e32 v160, 0x90, v132
	v_lshlrev_b32_e32 v160, 11, v160
	v_lshl_add_u64 v[162:163], v[134:135], 0, v[160:161]
	global_load_dwordx2 v[232:233], v[162:163], off
	global_load_dwordx2 v[234:235], v[162:163], off offset:32
	global_load_dwordx2 v[236:237], v[162:163], off offset:256
	global_load_dwordx2 v[238:239], v[162:163], off offset:288
	v_add_u32_e32 v160, 0xa0, v132
	v_lshlrev_b32_e32 v160, 11, v160
	v_lshl_add_u64 v[162:163], v[134:135], 0, v[160:161]
	global_load_dwordx2 v[240:241], v[162:163], off
	global_load_dwordx2 v[242:243], v[162:163], off offset:32
	global_load_dwordx2 v[244:245], v[162:163], off offset:256
	global_load_dwordx2 v[246:247], v[162:163], off offset:288
	v_add_u32_e32 v160, 0xb0, v132
	v_lshlrev_b32_e32 v160, 11, v160
	v_lshl_add_u64 v[162:163], v[134:135], 0, v[160:161]
	global_load_dwordx2 v[248:249], v[162:163], off
	global_load_dwordx2 v[250:251], v[162:163], off offset:32
	global_load_dwordx2 v[182:183], v[162:163], off offset:256
	global_load_dwordx2 v[184:185], v[162:163], off offset:288
	s_waitcnt vmcnt(0)
	v_and_b32_e32 v133, 63, v130
	v_lshlrev_b32_e32 v143, 2, v133
	v_xor_b32_e32 v0, 64, v143
	s_lshl_b32 s8, s9, 2
	s_add_i32 s10, s8, 16
	v_cmp_gt_u32_e32 vcc, 16, v133
	v_mov_b64_e32 v[138:139], v[192:193]
	v_lshlrev_b32_e32 v140, 16, v138
	v_and_b32_e32 v141, 0xffff0000, v138
	v_lshlrev_b32_e32 v138, 16, v139
	v_and_b32_e32 v139, 0xffff0000, v139
	v_pk_add_f32 v[128:129], v[128:129], v[138:139]
	v_pk_add_f32 v[126:127], v[126:127], v[140:141]
	s_nop 0
	v_cvt_pk_bf16_f32 v138, v126, v127
	v_cvt_pk_bf16_f32 v139, v128, v129
	v_mul_f32_e32 v127, v127, v127
	global_store_dwordx2 v[136:137], v[138:139], off
	v_fmac_f32_e32 v127, v126, v126
	v_fmac_f32_e32 v127, v128, v128
	v_fmac_f32_e32 v127, v129, v129
	v_mov_b64_e32 v[140:141], v[194:195]
	v_lshlrev_b32_e32 v138, 16, v140
	v_and_b32_e32 v139, 0xffff0000, v140
	v_lshlrev_b32_e32 v140, 16, v141
	v_and_b32_e32 v141, 0xffff0000, v141
	v_pk_add_f32 v[124:125], v[124:125], v[140:141]
	v_pk_add_f32 v[122:123], v[122:123], v[138:139]
	s_nop 0
	v_cvt_pk_bf16_f32 v138, v122, v123
	v_cvt_pk_bf16_f32 v139, v124, v125
	v_mul_f32_e32 v123, v123, v123
	global_store_dwordx2 v[136:137], v[138:139], off offset:32
	v_fmac_f32_e32 v123, v122, v122
	v_fmac_f32_e32 v123, v124, v124
	v_fmac_f32_e32 v123, v125, v125
	v_add_f32_e32 v122, v127, v123
	v_mov_b64_e32 v[140:141], v[196:197]
	v_lshlrev_b32_e32 v138, 16, v140
	v_and_b32_e32 v139, 0xffff0000, v140
	v_lshlrev_b32_e32 v140, 16, v141
	v_and_b32_e32 v141, 0xffff0000, v141
	v_pk_add_f32 v[120:121], v[120:121], v[140:141]
	v_pk_add_f32 v[118:119], v[118:119], v[138:139]
	s_nop 0
	v_cvt_pk_bf16_f32 v138, v118, v119
	v_cvt_pk_bf16_f32 v139, v120, v121
	v_mul_f32_e32 v119, v119, v119
	v_fmac_f32_e32 v119, v118, v118
	v_fmac_f32_e32 v119, v120, v120
	v_fmac_f32_e32 v119, v121, v121
	v_add_f32_e32 v122, v122, v119
	global_store_dwordx2 v[136:137], v[138:139], off offset:256
	v_mov_b64_e32 v[140:141], v[198:199]
	v_lshlrev_b32_e32 v118, 16, v140
	v_and_b32_e32 v119, 0xffff0000, v140
	v_pk_add_f32 v[118:119], v[114:115], v[118:119]
	v_lshlrev_b32_e32 v120, 16, v141
	v_and_b32_e32 v121, 0xffff0000, v141
	v_mul_f32_e32 v114, v119, v119
	v_pk_add_f32 v[120:121], v[116:117], v[120:121]
	v_fmac_f32_e32 v114, v118, v118
	v_fmac_f32_e32 v114, v120, v120
	v_fmac_f32_e32 v114, v121, v121
	v_add_f32_e32 v114, v122, v114
	ds_bpermute_b32 v115, v0, v114
	v_xor_b32_e32 v116, 0x80, v143
	v_cvt_pk_bf16_f32 v118, v118, v119
	v_cvt_pk_bf16_f32 v119, v120, v121
	global_store_dwordx2 v[136:137], v[118:119], off offset:288
	s_waitcnt lgkmcnt(0)
	v_add_f32_e32 v114, v114, v115
	ds_bpermute_b32 v115, v116, v114
	s_and_saveexec_b64 s[8:9], vcc
	s_cbranch_execz .LBB0_972
	s_waitcnt lgkmcnt(0)
	v_add_f32_e32 v114, v114, v115
	v_lshl_add_u32 v115, v132, 4, s10
	ds_write_b32 v115, v114
; __device__ __forceinline__ float bflo(unsigned w) { return __uint_as_float(w << 16); }
; __device__ __forceinline__ float bfhi(unsigned w) { return __uint_as_float(w & 0xffff0000u); }
; template <int MODE, bool PRE = false, bool NEXT = false> ...
;     ...
;       } else if constexpr (MODE == EP_RES) {
;         float* orow = (float*)e.out + (long)row * e.ldo + cbase;
;         const float* arow = (const float*)e.aux + (long)row * e.ldaux + cbase;
;         const u16* brow = (const u16*)e.aux + (long)row * e.ldaux + cbase;
;         u16* xrow = e.xb + (long)row * 1024 + cbase;
;         float part = 0.f;
; #pragma unroll
;         for (int bj = 0; bj < 2; ++bj)
; #pragma unroll
;           for (int n = 0; n < 2; ++n) {
;             f32x4 a;
;             if (e.auxbf) { const u32x2 w = *reinterpret_cast<const u32x2*>(brow + bj * 128 + n * 16); a = f32x4{bflo(w[0]), bfhi(w[0]), bflo(w[1]), bfhi(w[1])}; }
;             else a = *reinterpret_cast<const f32x4*>(arow + bj * 128 + n * 16);
;             a += acc[ai][bj][m][n];
;             if (e.out) *reinterpret_cast<f32x4*>(orow + bj * 128 + n * 16) = a;
;             if (e.xb) {
;               u32x2 w = {cvtpk(a[0], a[1]), cvtpk(a[2], a[3])};
;               *reinterpret_cast<u32x2*>(xrow + bj * 128 + n * 16) = w;
;               part += a[0] * a[0] + a[1] * a[1] + a[2] * a[2] + a[3] * a[3];
;             }
;           }
;         if (e.xb) {
;           part += __int_as_float(__builtin_amdgcn_ds_bpermute((lane ^ 16) << 2, __float_as_int(part)));
;           part += __int_as_float(__builtin_amdgcn_ds_bpermute((lane ^ 32) << 2, __float_as_int(part)));
;           if (fq == 0) reinterpret_cast<float*>(g_lds)[row * 4 + wc] = part;
;         }
.LBB0_972:
	s_or_b64 exec, exec, s[8:9]
	v_or_b32_e32 v114, 16, v132
	s_waitcnt lgkmcnt(0)
	v_ashrrev_i32_e32 v115, 31, v114
	v_lshlrev_b64 v[118:119], 11, v[114:115]
	v_lshl_add_u64 v[118:119], v[134:135], 0, v[118:119]
	v_mov_b64_e32 v[120:121], v[200:201]
	v_lshlrev_b32_e32 v122, 16, v120
	v_and_b32_e32 v123, 0xffff0000, v120
	v_lshlrev_b32_e32 v120, 16, v121
	v_and_b32_e32 v121, 0xffff0000, v121
	v_pk_add_f32 v[112:113], v[112:113], v[120:121]
	v_pk_add_f32 v[110:111], v[110:111], v[122:123]
	s_nop 0
	v_cvt_pk_bf16_f32 v120, v110, v111
	v_cvt_pk_bf16_f32 v121, v112, v113
	v_mul_f32_e32 v111, v111, v111
	global_store_dwordx2 v[118:119], v[120:121], off
	v_fmac_f32_e32 v111, v110, v110
	v_fmac_f32_e32 v111, v112, v112
	v_fmac_f32_e32 v111, v113, v113
	v_mov_b64_e32 v[122:123], v[202:203]
	v_lshlrev_b32_e32 v120, 16, v122
	v_and_b32_e32 v121, 0xffff0000, v122
	v_lshlrev_b32_e32 v122, 16, v123
	v_and_b32_e32 v123, 0xffff0000, v123
	v_pk_add_f32 v[108:109], v[108:109], v[122:123]
	v_pk_add_f32 v[106:107], v[106:107], v[120:121]
	s_nop 0
	v_cvt_pk_bf16_f32 v120, v106, v107
	v_cvt_pk_bf16_f32 v121, v108, v109
	v_mul_f32_e32 v107, v107, v107
	global_store_dwordx2 v[118:119], v[120:121], off offset:32
	v_fmac_f32_e32 v107, v106, v106
	v_fmac_f32_e32 v107, v108, v108
	v_fmac_f32_e32 v107, v109, v109
	v_add_f32_e32 v106, v111, v107
	v_mov_b64_e32 v[122:123], v[204:205]
	v_lshlrev_b32_e32 v120, 16, v122
	v_and_b32_e32 v121, 0xffff0000, v122
	v_lshlrev_b32_e32 v122, 16, v123
	v_and_b32_e32 v123, 0xffff0000, v123
	v_pk_add_f32 v[104:105], v[104:105], v[122:123]
	v_pk_add_f32 v[102:103], v[102:103], v[120:121]
	s_nop 0
	v_cvt_pk_bf16_f32 v120, v102, v103
	v_cvt_pk_bf16_f32 v121, v104, v105
	v_mul_f32_e32 v103, v103, v103
	v_fmac_f32_e32 v103, v102, v102
	v_fmac_f32_e32 v103, v104, v104
	v_fmac_f32_e32 v103, v105, v105
	v_add_f32_e32 v106, v106, v103
	global_store_dwordx2 v[118:119], v[120:121], off offset:256
	v_mov_b64_e32 v[122:123], v[206:207]
	v_lshlrev_b32_e32 v102, 16, v122
	v_and_b32_e32 v103, 0xffff0000, v122
	v_pk_add_f32 v[102:103], v[98:99], v[102:103]
	v_lshlrev_b32_e32 v104, 16, v123
	v_and_b32_e32 v105, 0xffff0000, v123
	v_mul_f32_e32 v98, v103, v103
	v_pk_add_f32 v[100:101], v[100:101], v[104:105]
	v_fmac_f32_e32 v98, v102, v102
	v_fmac_f32_e32 v98, v100, v100
	v_fmac_f32_e32 v98, v101, v101
	v_add_f32_e32 v98, v106, v98
	ds_bpermute_b32 v99, v0, v98
	v_cvt_pk_bf16_f32 v102, v102, v103
	v_cvt_pk_bf16_f32 v103, v100, v101
	global_store_dwordx2 v[118:119], v[102:103], off offset:288
	s_waitcnt lgkmcnt(0)
	v_add_f32_e32 v98, v98, v99
	ds_bpermute_b32 v99, v116, v98
	s_and_saveexec_b64 s[8:9], vcc
	s_cbranch_execz .LBB0_974
	s_waitcnt lgkmcnt(0)
	v_add_f32_e32 v98, v98, v99
	v_lshl_add_u32 v99, v114, 4, s10
	ds_write_b32 v99, v98
.LBB0_974:
	s_or_b64 exec, exec, s[8:9]
	v_or_b32_e32 v98, 32, v132
	s_waitcnt lgkmcnt(0)
	v_ashrrev_i32_e32 v99, 31, v98
	v_lshlrev_b64 v[100:101], 11, v[98:99]
	v_lshl_add_u64 v[100:101], v[134:135], 0, v[100:101]
	v_mov_b64_e32 v[102:103], v[208:209]
	v_lshlrev_b32_e32 v104, 16, v102
	v_and_b32_e32 v105, 0xffff0000, v102
	v_lshlrev_b32_e32 v102, 16, v103
	v_and_b32_e32 v103, 0xffff0000, v103
	v_pk_add_f32 v[96:97], v[96:97], v[102:103]
	v_pk_add_f32 v[94:95], v[94:95], v[104:105]
	s_nop 0
	v_cvt_pk_bf16_f32 v102, v94, v95
	v_cvt_pk_bf16_f32 v103, v96, v97
	v_mul_f32_e32 v95, v95, v95
	global_store_dwordx2 v[100:101], v[102:103], off
	v_fmac_f32_e32 v95, v94, v94
	v_fmac_f32_e32 v95, v96, v96
	v_fmac_f32_e32 v95, v97, v97
	v_mov_b64_e32 v[104:105], v[210:211]
	v_lshlrev_b32_e32 v102, 16, v104
	v_and_b32_e32 v103, 0xffff0000, v104
	v_lshlrev_b32_e32 v104, 16, v105
	v_and_b32_e32 v105, 0xffff0000, v105
	v_pk_add_f32 v[92:93], v[92:93], v[104:105]
	v_pk_add_f32 v[90:91], v[90:91], v[102:103]
	s_nop 0
	v_cvt_pk_bf16_f32 v102, v90, v91
	v_cvt_pk_bf16_f32 v103, v92, v93
	v_mul_f32_e32 v91, v91, v91
	global_store_dwordx2 v[100:101], v[102:103], off offset:32
	v_fmac_f32_e32 v91, v90, v90
	v_fmac_f32_e32 v91, v92, v92
	v_fmac_f32_e32 v91, v93, v93
	v_add_f32_e32 v90, v95, v91
	v_mov_b64_e32 v[104:105], v[212:213]
	v_lshlrev_b32_e32 v102, 16, v104
	v_and_b32_e32 v103, 0xffff0000, v104
	v_lshlrev_b32_e32 v104, 16, v105
	v_and_b32_e32 v105, 0xffff0000, v105
	v_pk_add_f32 v[88:89], v[88:89], v[104:105]
	v_pk_add_f32 v[86:87], v[86:87], v[102:103]
	s_nop 0
	v_cvt_pk_bf16_f32 v102, v86, v87
	v_cvt_pk_bf16_f32 v103, v88, v89
	v_mul_f32_e32 v87, v87, v87
	v_fmac_f32_e32 v87, v86, v86
	v_fmac_f32_e32 v87, v88, v88
	v_fmac_f32_e32 v87, v89, v89
	v_add_f32_e32 v90, v90, v87
	global_store_dwordx2 v[100:101], v[102:103], off offset:256
	v_mov_b64_e32 v[104:105], v[214:215]
	v_lshlrev_b32_e32 v86, 16, v104
	v_and_b32_e32 v87, 0xffff0000, v104
	v_pk_add_f32 v[86:87], v[82:83], v[86:87]
	v_lshlrev_b32_e32 v88, 16, v105
	v_and_b32_e32 v89, 0xffff0000, v105
	v_mul_f32_e32 v82, v87, v87
	v_pk_add_f32 v[84:85], v[84:85], v[88:89]
	v_fmac_f32_e32 v82, v86, v86
	v_fmac_f32_e32 v82, v84, v84
	v_fmac_f32_e32 v82, v85, v85
	v_add_f32_e32 v82, v90, v82
	ds_bpermute_b32 v83, v0, v82
	v_cvt_pk_bf16_f32 v86, v86, v87
	v_cvt_pk_bf16_f32 v87, v84, v85
	global_store_dwordx2 v[100:101], v[86:87], off offset:288
	s_waitcnt lgkmcnt(0)
	v_add_f32_e32 v82, v82, v83
	ds_bpermute_b32 v83, v116, v82
	s_and_saveexec_b64 s[8:9], vcc
	s_cbranch_execz .LBB0_976
	s_waitcnt lgkmcnt(0)
	v_add_f32_e32 v82, v82, v83
	v_lshl_add_u32 v83, v98, 4, s10
	ds_write_b32 v83, v82
; __device__ __forceinline__ float bflo(unsigned w) { return __uint_as_float(w << 16); }
; __device__ __forceinline__ float bfhi(unsigned w) { return __uint_as_float(w & 0xffff0000u); }
; template <int MODE, bool PRE = false, bool NEXT = false> ...
;     ...
;       } else if constexpr (MODE == EP_RES) {
;         float* orow = (float*)e.out + (long)row * e.ldo + cbase;
;         const float* arow = (const float*)e.aux + (long)row * e.ldaux + cbase;
;         const u16* brow = (const u16*)e.aux + (long)row * e.ldaux + cbase;
;         u16* xrow = e.xb + (long)row * 1024 + cbase;
;         float part = 0.f;
; #pragma unroll
;         for (int bj = 0; bj < 2; ++bj)
; #pragma unroll
;           for (int n = 0; n < 2; ++n) {
;             f32x4 a;
;             if (e.auxbf) { const u32x2 w = *reinterpret_cast<const u32x2*>(brow + bj * 128 + n * 16); a = f32x4{bflo(w[0]), bfhi(w[0]), bflo(w[1]), bfhi(w[1])}; }
;             else a = *reinterpret_cast<const f32x4*>(arow + bj * 128 + n * 16);
;             a += acc[ai][bj][m][n];
;             if (e.out) *reinterpret_cast<f32x4*>(orow + bj * 128 + n * 16) = a;
;             if (e.xb) {
;               u32x2 w = {cvtpk(a[0], a[1]), cvtpk(a[2], a[3])};
;               *reinterpret_cast<u32x2*>(xrow + bj * 128 + n * 16) = w;
;               part += a[0] * a[0] + a[1] * a[1] + a[2] * a[2] + a[3] * a[3];
;             }
;           }
;         if (e.xb) {
;           part += __int_as_float(__builtin_amdgcn_ds_bpermute((lane ^ 16) << 2, __float_as_int(part)));
;           part += __int_as_float(__builtin_amdgcn_ds_bpermute((lane ^ 32) << 2, __float_as_int(part)));
;           if (fq == 0) reinterpret_cast<float*>(g_lds)[row * 4 + wc] = part;
;         }
.LBB0_976:
	s_or_b64 exec, exec, s[8:9]
	v_or_b32_e32 v82, 48, v132
	s_waitcnt lgkmcnt(0)
	v_ashrrev_i32_e32 v83, 31, v82
	v_lshlrev_b64 v[84:85], 11, v[82:83]
	v_lshl_add_u64 v[84:85], v[134:135], 0, v[84:85]
	v_mov_b64_e32 v[86:87], v[216:217]
	v_lshlrev_b32_e32 v88, 16, v86
	v_and_b32_e32 v89, 0xffff0000, v86
	v_lshlrev_b32_e32 v86, 16, v87
	v_and_b32_e32 v87, 0xffff0000, v87
	v_pk_add_f32 v[80:81], v[80:81], v[86:87]
	v_pk_add_f32 v[78:79], v[78:79], v[88:89]
	s_nop 0
	v_cvt_pk_bf16_f32 v86, v78, v79
	v_cvt_pk_bf16_f32 v87, v80, v81
	v_mul_f32_e32 v79, v79, v79
	global_store_dwordx2 v[84:85], v[86:87], off
	v_fmac_f32_e32 v79, v78, v78
	v_fmac_f32_e32 v79, v80, v80
	v_fmac_f32_e32 v79, v81, v81
	v_mov_b64_e32 v[88:89], v[218:219]
	v_lshlrev_b32_e32 v86, 16, v88
	v_and_b32_e32 v87, 0xffff0000, v88
	v_lshlrev_b32_e32 v88, 16, v89
	v_and_b32_e32 v89, 0xffff0000, v89
	v_pk_add_f32 v[76:77], v[76:77], v[88:89]
	v_pk_add_f32 v[74:75], v[74:75], v[86:87]
	s_nop 0
	v_cvt_pk_bf16_f32 v86, v74, v75
	v_cvt_pk_bf16_f32 v87, v76, v77
	v_mul_f32_e32 v75, v75, v75
	global_store_dwordx2 v[84:85], v[86:87], off offset:32
	v_fmac_f32_e32 v75, v74, v74
	v_fmac_f32_e32 v75, v76, v76
	v_fmac_f32_e32 v75, v77, v77
	v_add_f32_e32 v74, v79, v75
	v_mov_b64_e32 v[88:89], v[220:221]
	v_lshlrev_b32_e32 v86, 16, v88
	v_and_b32_e32 v87, 0xffff0000, v88
	v_lshlrev_b32_e32 v88, 16, v89
	v_and_b32_e32 v89, 0xffff0000, v89
	v_pk_add_f32 v[72:73], v[72:73], v[88:89]
	v_pk_add_f32 v[70:71], v[70:71], v[86:87]
	s_nop 0
	v_cvt_pk_bf16_f32 v86, v70, v71
	v_cvt_pk_bf16_f32 v87, v72, v73
	v_mul_f32_e32 v71, v71, v71
	v_fmac_f32_e32 v71, v70, v70
	v_fmac_f32_e32 v71, v72, v72
	v_fmac_f32_e32 v71, v73, v73
	v_add_f32_e32 v74, v74, v71
	global_store_dwordx2 v[84:85], v[86:87], off offset:256
	v_mov_b64_e32 v[88:89], v[222:223]
	v_lshlrev_b32_e32 v70, 16, v88
	v_and_b32_e32 v71, 0xffff0000, v88
	v_pk_add_f32 v[70:71], v[66:67], v[70:71]
	v_lshlrev_b32_e32 v72, 16, v89
	v_and_b32_e32 v73, 0xffff0000, v89
	v_mul_f32_e32 v66, v71, v71
	v_pk_add_f32 v[68:69], v[68:69], v[72:73]
	v_fmac_f32_e32 v66, v70, v70
	v_fmac_f32_e32 v66, v68, v68
	v_fmac_f32_e32 v66, v69, v69
	v_add_f32_e32 v66, v74, v66
	ds_bpermute_b32 v67, v0, v66
	v_cvt_pk_bf16_f32 v70, v70, v71
	v_cvt_pk_bf16_f32 v71, v68, v69
	global_store_dwordx2 v[84:85], v[70:71], off offset:288
	s_waitcnt lgkmcnt(0)
	v_add_f32_e32 v66, v66, v67
	ds_bpermute_b32 v67, v116, v66
	s_and_saveexec_b64 s[8:9], vcc
	s_cbranch_execz .LBB0_978
	s_waitcnt lgkmcnt(0)
	v_add_f32_e32 v66, v66, v67
	v_lshl_add_u32 v67, v82, 4, s10
	ds_write_b32 v67, v66
.LBB0_978:
	s_or_b64 exec, exec, s[8:9]
	v_add_u32_e32 v66, 0x80, v132
	s_waitcnt lgkmcnt(0)
	v_ashrrev_i32_e32 v67, 31, v66
	v_lshlrev_b64 v[68:69], 11, v[66:67]
	v_lshl_add_u64 v[68:69], v[134:135], 0, v[68:69]
	v_mov_b64_e32 v[70:71], v[224:225]
	v_lshlrev_b32_e32 v72, 16, v70
	v_and_b32_e32 v73, 0xffff0000, v70
	v_lshlrev_b32_e32 v70, 16, v71
	v_and_b32_e32 v71, 0xffff0000, v71
	v_pk_add_f32 v[64:65], v[64:65], v[70:71]
	v_pk_add_f32 v[62:63], v[62:63], v[72:73]
	s_nop 0
	v_cvt_pk_bf16_f32 v70, v62, v63
	v_cvt_pk_bf16_f32 v71, v64, v65
	v_mul_f32_e32 v63, v63, v63
	global_store_dwordx2 v[68:69], v[70:71], off
	v_fmac_f32_e32 v63, v62, v62
	v_fmac_f32_e32 v63, v64, v64
	v_fmac_f32_e32 v63, v65, v65
	v_mov_b64_e32 v[72:73], v[226:227]
	v_lshlrev_b32_e32 v70, 16, v72
	v_and_b32_e32 v71, 0xffff0000, v72
	v_lshlrev_b32_e32 v72, 16, v73
	v_and_b32_e32 v73, 0xffff0000, v73
	v_pk_add_f32 v[60:61], v[60:61], v[72:73]
	v_pk_add_f32 v[58:59], v[58:59], v[70:71]
	s_nop 0
	v_cvt_pk_bf16_f32 v70, v58, v59
	v_cvt_pk_bf16_f32 v71, v60, v61
	v_mul_f32_e32 v59, v59, v59
	global_store_dwordx2 v[68:69], v[70:71], off offset:32
	v_fmac_f32_e32 v59, v58, v58
	v_fmac_f32_e32 v59, v60, v60
	v_fmac_f32_e32 v59, v61, v61
	v_add_f32_e32 v58, v63, v59
	v_mov_b64_e32 v[72:73], v[228:229]
	v_lshlrev_b32_e32 v70, 16, v72
	v_and_b32_e32 v71, 0xffff0000, v72
	v_lshlrev_b32_e32 v72, 16, v73
	v_and_b32_e32 v73, 0xffff0000, v73
	v_pk_add_f32 v[56:57], v[56:57], v[72:73]
	v_pk_add_f32 v[54:55], v[54:55], v[70:71]
	s_nop 0
	v_cvt_pk_bf16_f32 v70, v54, v55
	v_cvt_pk_bf16_f32 v71, v56, v57
	v_mul_f32_e32 v55, v55, v55
	v_fmac_f32_e32 v55, v54, v54
	v_fmac_f32_e32 v55, v56, v56
	v_fmac_f32_e32 v55, v57, v57
	v_add_f32_e32 v58, v58, v55
	global_store_dwordx2 v[68:69], v[70:71], off offset:256
	v_mov_b64_e32 v[72:73], v[230:231]
	v_lshlrev_b32_e32 v54, 16, v72
	v_and_b32_e32 v55, 0xffff0000, v72
	v_pk_add_f32 v[54:55], v[50:51], v[54:55]
	v_lshlrev_b32_e32 v56, 16, v73
	v_and_b32_e32 v57, 0xffff0000, v73
	v_mul_f32_e32 v50, v55, v55
	v_pk_add_f32 v[52:53], v[52:53], v[56:57]
	v_fmac_f32_e32 v50, v54, v54
	v_fmac_f32_e32 v50, v52, v52
	v_fmac_f32_e32 v50, v53, v53
	v_add_f32_e32 v50, v58, v50
	ds_bpermute_b32 v51, v0, v50
	v_cvt_pk_bf16_f32 v54, v54, v55
	v_cvt_pk_bf16_f32 v55, v52, v53
	global_store_dwordx2 v[68:69], v[54:55], off offset:288
	s_waitcnt lgkmcnt(0)
	v_add_f32_e32 v50, v50, v51
	ds_bpermute_b32 v51, v116, v50
	s_and_saveexec_b64 s[8:9], vcc
	s_cbranch_execz .LBB0_980
	s_waitcnt lgkmcnt(0)
	v_add_f32_e32 v50, v50, v51
	v_lshl_add_u32 v51, v66, 4, s10
	ds_write_b32 v51, v50
; __device__ __forceinline__ float bflo(unsigned w) { return __uint_as_float(w << 16); }
; __device__ __forceinline__ float bfhi(unsigned w) { return __uint_as_float(w & 0xffff0000u); }
; template <int MODE, bool PRE = false, bool NEXT = false> ...
;     ...
;       } else if constexpr (MODE == EP_RES) {
;         float* orow = (float*)e.out + (long)row * e.ldo + cbase;
;         const float* arow = (const float*)e.aux + (long)row * e.ldaux + cbase;
;         const u16* brow = (const u16*)e.aux + (long)row * e.ldaux + cbase;
;         u16* xrow = e.xb + (long)row * 1024 + cbase;
;         float part = 0.f;
; #pragma unroll
;         for (int bj = 0; bj < 2; ++bj)
; #pragma unroll
;           for (int n = 0; n < 2; ++n) {
;             f32x4 a;
;             if (e.auxbf) { const u32x2 w = *reinterpret_cast<const u32x2*>(brow + bj * 128 + n * 16); a = f32x4{bflo(w[0]), bfhi(w[0]), bflo(w[1]), bfhi(w[1])}; }
;             else a = *reinterpret_cast<const f32x4*>(arow + bj * 128 + n * 16);
;             a += acc[ai][bj][m][n];
;             if (e.out) *reinterpret_cast<f32x4*>(orow + bj * 128 + n * 16) = a;
;             if (e.xb) {
;               u32x2 w = {cvtpk(a[0], a[1]), cvtpk(a[2], a[3])};
;               *reinterpret_cast<u32x2*>(xrow + bj * 128 + n * 16) = w;
;               part += a[0] * a[0] + a[1] * a[1] + a[2] * a[2] + a[3] * a[3];
;             }
;           }
;         if (e.xb) {
;           part += __int_as_float(__builtin_amdgcn_ds_bpermute((lane ^ 16) << 2, __float_as_int(part)));
;           part += __int_as_float(__builtin_amdgcn_ds_bpermute((lane ^ 32) << 2, __float_as_int(part)));
;           if (fq == 0) reinterpret_cast<float*>(g_lds)[row * 4 + wc] = part;
;         }
.LBB0_980:
	s_or_b64 exec, exec, s[8:9]
	v_add_u32_e32 v50, 0x90, v132
	s_waitcnt lgkmcnt(0)
	v_ashrrev_i32_e32 v51, 31, v50
	v_lshlrev_b64 v[52:53], 11, v[50:51]
	v_lshl_add_u64 v[52:53], v[134:135], 0, v[52:53]
	v_mov_b64_e32 v[54:55], v[232:233]
	v_lshlrev_b32_e32 v56, 16, v54
	v_and_b32_e32 v57, 0xffff0000, v54
	v_lshlrev_b32_e32 v54, 16, v55
	v_and_b32_e32 v55, 0xffff0000, v55
	v_pk_add_f32 v[48:49], v[48:49], v[54:55]
	v_pk_add_f32 v[46:47], v[46:47], v[56:57]
	s_nop 0
	v_cvt_pk_bf16_f32 v54, v46, v47
	v_cvt_pk_bf16_f32 v55, v48, v49
	v_mul_f32_e32 v47, v47, v47
	global_store_dwordx2 v[52:53], v[54:55], off
	v_fmac_f32_e32 v47, v46, v46
	v_fmac_f32_e32 v47, v48, v48
	v_fmac_f32_e32 v47, v49, v49
	v_mov_b64_e32 v[56:57], v[234:235]
	v_lshlrev_b32_e32 v54, 16, v56
	v_and_b32_e32 v55, 0xffff0000, v56
	v_lshlrev_b32_e32 v56, 16, v57
	v_and_b32_e32 v57, 0xffff0000, v57
	v_pk_add_f32 v[44:45], v[44:45], v[56:57]
	v_pk_add_f32 v[42:43], v[42:43], v[54:55]
	s_nop 0
	v_cvt_pk_bf16_f32 v54, v42, v43
	v_cvt_pk_bf16_f32 v55, v44, v45
	v_mul_f32_e32 v43, v43, v43
	global_store_dwordx2 v[52:53], v[54:55], off offset:32
	v_fmac_f32_e32 v43, v42, v42
	v_fmac_f32_e32 v43, v44, v44
	v_fmac_f32_e32 v43, v45, v45
	v_add_f32_e32 v42, v47, v43
	v_mov_b64_e32 v[56:57], v[236:237]
	v_lshlrev_b32_e32 v54, 16, v56
	v_and_b32_e32 v55, 0xffff0000, v56
	v_lshlrev_b32_e32 v56, 16, v57
	v_and_b32_e32 v57, 0xffff0000, v57
	v_pk_add_f32 v[40:41], v[40:41], v[56:57]
	v_pk_add_f32 v[38:39], v[38:39], v[54:55]
	s_nop 0
	v_cvt_pk_bf16_f32 v54, v38, v39
	v_cvt_pk_bf16_f32 v55, v40, v41
	v_mul_f32_e32 v39, v39, v39
	v_fmac_f32_e32 v39, v38, v38
	v_fmac_f32_e32 v39, v40, v40
	v_fmac_f32_e32 v39, v41, v41
	v_add_f32_e32 v42, v42, v39
	global_store_dwordx2 v[52:53], v[54:55], off offset:256
	v_mov_b64_e32 v[56:57], v[238:239]
	v_lshlrev_b32_e32 v38, 16, v56
	v_and_b32_e32 v39, 0xffff0000, v56
	v_pk_add_f32 v[38:39], v[34:35], v[38:39]
	v_lshlrev_b32_e32 v40, 16, v57
	v_and_b32_e32 v41, 0xffff0000, v57
	v_mul_f32_e32 v34, v39, v39
	v_pk_add_f32 v[36:37], v[36:37], v[40:41]
	v_fmac_f32_e32 v34, v38, v38
	v_fmac_f32_e32 v34, v36, v36
	v_fmac_f32_e32 v34, v37, v37
	v_add_f32_e32 v34, v42, v34
	ds_bpermute_b32 v35, v0, v34
	v_cvt_pk_bf16_f32 v38, v38, v39
	v_cvt_pk_bf16_f32 v39, v36, v37
	global_store_dwordx2 v[52:53], v[38:39], off offset:288
	s_waitcnt lgkmcnt(0)
	v_add_f32_e32 v34, v34, v35
	ds_bpermute_b32 v35, v116, v34
	s_and_saveexec_b64 s[8:9], vcc
	s_cbranch_execz .LBB0_982
	s_waitcnt lgkmcnt(0)
	v_add_f32_e32 v34, v34, v35
	v_lshl_add_u32 v35, v50, 4, s10
	ds_write_b32 v35, v34
; __device__ __forceinline__ float bflo(unsigned w) { return __uint_as_float(w << 16); }
; __device__ __forceinline__ float bfhi(unsigned w) { return __uint_as_float(w & 0xffff0000u); }
; template <int MODE, bool PRE = false, bool NEXT = false> ...
;     ...
;       } else if constexpr (MODE == EP_RES) {
;         float* orow = (float*)e.out + (long)row * e.ldo + cbase;
;         const float* arow = (const float*)e.aux + (long)row * e.ldaux + cbase;
;         const u16* brow = (const u16*)e.aux + (long)row * e.ldaux + cbase;
;         u16* xrow = e.xb + (long)row * 1024 + cbase;
;         float part = 0.f;
; #pragma unroll
;         for (int bj = 0; bj < 2; ++bj)
; #pragma unroll
;           for (int n = 0; n < 2; ++n) {
;             f32x4 a;
;             if (e.auxbf) { const u32x2 w = *reinterpret_cast<const u32x2*>(brow + bj * 128 + n * 16); a = f32x4{bflo(w[0]), bfhi(w[0]), bflo(w[1]), bfhi(w[1])}; }
;             else a = *reinterpret_cast<const f32x4*>(arow + bj * 128 + n * 16);
;             a += acc[ai][bj][m][n];
;             if (e.out) *reinterpret_cast<f32x4*>(orow + bj * 128 + n * 16) = a;
;             if (e.xb) {
;               u32x2 w = {cvtpk(a[0], a[1]), cvtpk(a[2], a[3])};
;               *reinterpret_cast<u32x2*>(xrow + bj * 128 + n * 16) = w;
;               part += a[0] * a[0] + a[1] * a[1] + a[2] * a[2] + a[3] * a[3];
;             }
;           }
;         if (e.xb) {
;           part += __int_as_float(__builtin_amdgcn_ds_bpermute((lane ^ 16) << 2, __float_as_int(part)));
;           part += __int_as_float(__builtin_amdgcn_ds_bpermute((lane ^ 32) << 2, __float_as_int(part)));
;           if (fq == 0) reinterpret_cast<float*>(g_lds)[row * 4 + wc] = part;
;         }
.LBB0_982:
	s_or_b64 exec, exec, s[8:9]
	v_add_u32_e32 v34, 0xa0, v132
	s_waitcnt lgkmcnt(0)
	v_ashrrev_i32_e32 v35, 31, v34
	v_lshlrev_b64 v[36:37], 11, v[34:35]
	v_lshl_add_u64 v[36:37], v[134:135], 0, v[36:37]
	v_mov_b64_e32 v[38:39], v[240:241]
	v_lshlrev_b32_e32 v40, 16, v38
	v_and_b32_e32 v41, 0xffff0000, v38
	v_lshlrev_b32_e32 v38, 16, v39
	v_and_b32_e32 v39, 0xffff0000, v39
	v_pk_add_f32 v[32:33], v[32:33], v[38:39]
	v_pk_add_f32 v[30:31], v[30:31], v[40:41]
	s_nop 0
	v_cvt_pk_bf16_f32 v38, v30, v31
	v_cvt_pk_bf16_f32 v39, v32, v33
	v_mul_f32_e32 v31, v31, v31
	global_store_dwordx2 v[36:37], v[38:39], off
	v_fmac_f32_e32 v31, v30, v30
	v_fmac_f32_e32 v31, v32, v32
	v_fmac_f32_e32 v31, v33, v33
	v_mov_b64_e32 v[40:41], v[242:243]
	v_lshlrev_b32_e32 v38, 16, v40
	v_and_b32_e32 v39, 0xffff0000, v40
	v_lshlrev_b32_e32 v40, 16, v41
	v_and_b32_e32 v41, 0xffff0000, v41
	v_pk_add_f32 v[28:29], v[28:29], v[40:41]
	v_pk_add_f32 v[26:27], v[26:27], v[38:39]
	s_nop 0
	v_cvt_pk_bf16_f32 v38, v26, v27
	v_cvt_pk_bf16_f32 v39, v28, v29
	v_mul_f32_e32 v27, v27, v27
	global_store_dwordx2 v[36:37], v[38:39], off offset:32
	v_fmac_f32_e32 v27, v26, v26
	v_fmac_f32_e32 v27, v28, v28
	v_fmac_f32_e32 v27, v29, v29
	v_add_f32_e32 v26, v31, v27
	v_mov_b64_e32 v[40:41], v[244:245]
	v_lshlrev_b32_e32 v38, 16, v40
	v_and_b32_e32 v39, 0xffff0000, v40
	v_lshlrev_b32_e32 v40, 16, v41
	v_and_b32_e32 v41, 0xffff0000, v41
	v_pk_add_f32 v[24:25], v[24:25], v[40:41]
	v_pk_add_f32 v[22:23], v[22:23], v[38:39]
	s_nop 0
	v_cvt_pk_bf16_f32 v38, v22, v23
	v_cvt_pk_bf16_f32 v39, v24, v25
	v_mul_f32_e32 v23, v23, v23
	v_fmac_f32_e32 v23, v22, v22
	v_fmac_f32_e32 v23, v24, v24
	v_fmac_f32_e32 v23, v25, v25
	v_add_f32_e32 v26, v26, v23
	global_store_dwordx2 v[36:37], v[38:39], off offset:256
	v_mov_b64_e32 v[40:41], v[246:247]
	v_lshlrev_b32_e32 v22, 16, v40
	v_and_b32_e32 v23, 0xffff0000, v40
	v_pk_add_f32 v[22:23], v[18:19], v[22:23]
	v_lshlrev_b32_e32 v24, 16, v41
	v_and_b32_e32 v25, 0xffff0000, v41
	v_mul_f32_e32 v18, v23, v23
	v_pk_add_f32 v[20:21], v[20:21], v[24:25]
	v_fmac_f32_e32 v18, v22, v22
	v_fmac_f32_e32 v18, v20, v20
	v_fmac_f32_e32 v18, v21, v21
	v_add_f32_e32 v18, v26, v18
	ds_bpermute_b32 v19, v0, v18
	v_cvt_pk_bf16_f32 v22, v22, v23
	v_cvt_pk_bf16_f32 v23, v20, v21
	global_store_dwordx2 v[36:37], v[22:23], off offset:288
	s_waitcnt lgkmcnt(0)
	v_add_f32_e32 v18, v18, v19
	ds_bpermute_b32 v19, v116, v18
	s_and_saveexec_b64 s[8:9], vcc
	s_cbranch_execz .LBB0_984
	s_waitcnt lgkmcnt(0)
	v_add_f32_e32 v18, v18, v19
	v_lshl_add_u32 v19, v34, 4, s10
	ds_write_b32 v19, v18
.LBB0_984:
	s_or_b64 exec, exec, s[8:9]
	v_add_u32_e32 v18, 0xb0, v132
	s_waitcnt lgkmcnt(0)
	v_ashrrev_i32_e32 v19, 31, v18
	v_lshlrev_b64 v[20:21], 11, v[18:19]
	v_lshl_add_u64 v[20:21], v[134:135], 0, v[20:21]
	v_mov_b64_e32 v[22:23], v[248:249]
	v_lshlrev_b32_e32 v24, 16, v22
	v_and_b32_e32 v25, 0xffff0000, v22
	v_lshlrev_b32_e32 v22, 16, v23
	v_and_b32_e32 v23, 0xffff0000, v23
	v_pk_add_f32 v[16:17], v[16:17], v[22:23]
	v_pk_add_f32 v[14:15], v[14:15], v[24:25]
	s_nop 0
	v_cvt_pk_bf16_f32 v22, v14, v15
	v_cvt_pk_bf16_f32 v23, v16, v17
	v_mul_f32_e32 v15, v15, v15
	global_store_dwordx2 v[20:21], v[22:23], off
	v_fmac_f32_e32 v15, v14, v14
	v_fmac_f32_e32 v15, v16, v16
	v_fmac_f32_e32 v15, v17, v17
	v_mov_b64_e32 v[24:25], v[250:251]
	v_lshlrev_b32_e32 v22, 16, v24
	v_and_b32_e32 v23, 0xffff0000, v24
	v_lshlrev_b32_e32 v24, 16, v25
	v_and_b32_e32 v25, 0xffff0000, v25
	v_pk_add_f32 v[12:13], v[12:13], v[24:25]
	v_pk_add_f32 v[10:11], v[10:11], v[22:23]
	s_nop 0
	v_cvt_pk_bf16_f32 v22, v10, v11
	v_cvt_pk_bf16_f32 v23, v12, v13
	v_mul_f32_e32 v11, v11, v11
	global_store_dwordx2 v[20:21], v[22:23], off offset:32
	v_fmac_f32_e32 v11, v10, v10
	v_fmac_f32_e32 v11, v12, v12
	v_fmac_f32_e32 v11, v13, v13
	v_add_f32_e32 v10, v15, v11
	v_mov_b64_e32 v[24:25], v[182:183]
	v_lshlrev_b32_e32 v22, 16, v24
	v_and_b32_e32 v23, 0xffff0000, v24
	v_lshlrev_b32_e32 v24, 16, v25
	v_and_b32_e32 v25, 0xffff0000, v25
	v_pk_add_f32 v[8:9], v[8:9], v[24:25]
	v_pk_add_f32 v[6:7], v[6:7], v[22:23]
	s_nop 0
	v_cvt_pk_bf16_f32 v22, v6, v7
	v_cvt_pk_bf16_f32 v23, v8, v9
	v_mul_f32_e32 v7, v7, v7
	v_fmac_f32_e32 v7, v6, v6
	v_fmac_f32_e32 v7, v8, v8
	v_fmac_f32_e32 v7, v9, v9
	v_add_f32_e32 v10, v10, v7
	global_store_dwordx2 v[20:21], v[22:23], off offset:256
	v_mov_b64_e32 v[24:25], v[184:185]
	v_lshlrev_b32_e32 v6, 16, v24
	v_and_b32_e32 v7, 0xffff0000, v24
	v_pk_add_f32 v[6:7], v[2:3], v[6:7]
	v_lshlrev_b32_e32 v8, 16, v25
	v_and_b32_e32 v9, 0xffff0000, v25
	v_mul_f32_e32 v2, v7, v7
	v_pk_add_f32 v[4:5], v[4:5], v[8:9]
	v_fmac_f32_e32 v2, v6, v6
	v_fmac_f32_e32 v2, v4, v4
	v_fmac_f32_e32 v2, v5, v5
	v_add_f32_e32 v2, v10, v2
	ds_bpermute_b32 v0, v0, v2
	v_cvt_pk_bf16_f32 v6, v6, v7
	v_cvt_pk_bf16_f32 v7, v4, v5
	global_store_dwordx2 v[20:21], v[6:7], off offset:288
	s_waitcnt lgkmcnt(0)
	v_add_f32_e32 v0, v2, v0
	ds_bpermute_b32 v2, v116, v0
	s_and_saveexec_b64 s[8:9], vcc
	s_cbranch_execz .LBB0_986
	s_waitcnt lgkmcnt(0)
	v_add_f32_e32 v0, v0, v2
	v_lshl_add_u32 v2, v18, 4, s10
	ds_write_b32 v2, v0
